# scan loop: batch-ahead prefetch of Z rows (16 loads in flight, double-buffered regs), same arithmetic
# speedup vs baseline: 1.0109x; 1.0109x over previous
.LBB0_190:
	s_ashr_i32 s4, s4, 2
	v_lshl_or_b32 v4, s4, 7, v2
	v_ashrrev_i32_e32 v5, 31, v4
	v_lshl_add_u64 v[4:5], v[4:5], 2, s[0:1]
	global_load_dwordx2 v[4:5], v[4:5], off
	s_lshl_b32 s5, s3, 9
	s_and_b32 s8, s5, 0x60000
	s_ashr_i32 s5, s4, 31
	s_mul_hi_i32 s6, s4, 0x140000
	s_mul_i32 s7, s4, 0x140000
	s_lshl_b64 s[4:5], s[4:5], 19
	v_mov_b32_e32 v9, s6
	v_or_b32_e32 v8, s7, v2
	s_bfe_u32 s6, s3, 0x20008
	s_or_b32 s4, s4, s8
	v_mov_b32_e32 v12, 0
	v_mad_u64_u32 v[8:9], s[6:7], s6, v183, v[8:9]
	v_lshl_add_u64 v[10:11], s[4:5], 0, v[0:1]
	s_movk_i32 s4, 0x100
	v_mov_b32_e32 v13, v12
	s_waitcnt vmcnt(0)
	v_pk_mov_b32 v[6:7], v[4:5], v[4:5] op_sel:[1,0]
	v_lshl_add_u64 v[14:15], s[76:77], 0, v[10:11]
	global_load_dword v26, v[14:15], off offset:-2048
	global_load_dword v27, v[14:15], off offset:-1792
	global_load_dword v28, v[14:15], off offset:-1536
	global_load_dword v29, v[14:15], off offset:-1280
	global_load_dword v30, v[14:15], off offset:-1024
	global_load_dword v31, v[14:15], off offset:-768
	global_load_dword v32, v[14:15], off offset:-512
	global_load_dword v33, v[14:15], off offset:-256
	global_load_dword v34, v[14:15], off
	global_load_dword v35, v[14:15], off offset:256
	global_load_dword v36, v[14:15], off offset:512
	global_load_dword v37, v[14:15], off offset:768
	global_load_dword v38, v[14:15], off offset:1024
	global_load_dword v39, v[14:15], off offset:1280
	global_load_dword v40, v[14:15], off offset:1536
	global_load_dword v41, v[14:15], off offset:1792
	v_lshl_add_u64 v[10:11], v[10:11], 0, s[12:13]
	s_waitcnt vmcnt(0)
.Lsc_loop:
	s_waitcnt vmcnt(16)
	v_lshl_add_u64 v[14:15], s[76:77], 0, v[10:11]
	global_load_dword v42, v[14:15], off offset:-2048
	global_load_dword v43, v[14:15], off offset:-1792
	global_load_dword v44, v[14:15], off offset:-1536
	global_load_dword v45, v[14:15], off offset:-1280
	global_load_dword v46, v[14:15], off offset:-1024
	global_load_dword v47, v[14:15], off offset:-768
	global_load_dword v48, v[14:15], off offset:-512
	global_load_dword v49, v[14:15], off offset:-256
	global_load_dword v50, v[14:15], off
	global_load_dword v51, v[14:15], off offset:256
	global_load_dword v52, v[14:15], off offset:512
	global_load_dword v53, v[14:15], off offset:768
	global_load_dword v54, v[14:15], off offset:1024
	global_load_dword v55, v[14:15], off offset:1280
	global_load_dword v56, v[14:15], off offset:1536
	global_load_dword v57, v[14:15], off offset:1792
	v_lshl_add_u64 v[10:11], v[10:11], 0, s[12:13]
	v_lshl_add_u64 v[16:17], s[76:77], 0, v[8:9]
	v_add_co_u32_e32 v20, vcc, 0xfa00000, v16
	s_mov_b32 s5, 0xfa01000
	s_nop 0
	v_addc_co_u32_e32 v21, vcc, 0, v17, vcc
	v_add_co_u32_e32 v58, vcc, s5, v16
	s_mov_b32 s5, 0xfa02000
	s_nop 0
	v_addc_co_u32_e32 v59, vcc, 0, v17, vcc
	v_add_co_u32_e32 v60, vcc, s5, v16
	s_nop 1
	v_addc_co_u32_e32 v61, vcc, 0, v17, vcc
	v_lshl_add_u64 v[8:9], v[8:9], 0, s[62:63]
	v_cvt_pk_bf16_f32 v3, v12, v13
	v_pk_mul_f32 v[22:23], v[6:7], v[12:13] op_sel:[0,1]
	global_store_short v[20:21], v3, off offset:1024
	global_store_short_d16_hi v[20:21], v3, off offset:1152
	v_pk_fma_f32 v[24:25], v[4:5], v[12:13], v[22:23] neg_lo:[0,0,1] neg_hi:[0,0,1]
	v_pk_fma_f32 v[12:13], v[4:5], v[12:13], v[22:23] op_sel_hi:[1,0,1]
	s_nop 0
	v_mov_b32_e32 v25, v13
	v_pk_add_f32 v[12:13], v[24:25], v[26:27]
	v_cvt_pk_bf16_f32 v3, v12, v13
	v_pk_mul_f32 v[22:23], v[6:7], v[12:13] op_sel:[0,1]
	global_store_short v[20:21], v3, off offset:2304
	global_store_short_d16_hi v[20:21], v3, off offset:2432
	v_pk_fma_f32 v[24:25], v[4:5], v[12:13], v[22:23] neg_lo:[0,0,1] neg_hi:[0,0,1]
	v_pk_fma_f32 v[12:13], v[4:5], v[12:13], v[22:23] op_sel_hi:[1,0,1]
	s_nop 0
	v_mov_b32_e32 v25, v13
	v_pk_add_f32 v[12:13], v[24:25], v[28:29]
	v_cvt_pk_bf16_f32 v3, v12, v13
	v_pk_mul_f32 v[22:23], v[6:7], v[12:13] op_sel:[0,1]
	global_store_short v[20:21], v3, off offset:3584
	global_store_short_d16_hi v[20:21], v3, off offset:3712
	v_pk_fma_f32 v[24:25], v[4:5], v[12:13], v[22:23] neg_lo:[0,0,1] neg_hi:[0,0,1]
	v_pk_fma_f32 v[12:13], v[4:5], v[12:13], v[22:23] op_sel_hi:[1,0,1]
	s_nop 0
	v_mov_b32_e32 v25, v13
	v_pk_add_f32 v[12:13], v[24:25], v[30:31]
	v_cvt_pk_bf16_f32 v3, v12, v13
	v_pk_mul_f32 v[22:23], v[6:7], v[12:13] op_sel:[0,1]
	global_store_short v[58:59], v3, off offset:768
	global_store_short_d16_hi v[58:59], v3, off offset:896
	v_pk_fma_f32 v[24:25], v[4:5], v[12:13], v[22:23] neg_lo:[0,0,1] neg_hi:[0,0,1]
	v_pk_fma_f32 v[12:13], v[4:5], v[12:13], v[22:23] op_sel_hi:[1,0,1]
	s_nop 0
	v_mov_b32_e32 v25, v13
	v_pk_add_f32 v[12:13], v[24:25], v[32:33]
	v_cvt_pk_bf16_f32 v3, v12, v13
	v_pk_mul_f32 v[22:23], v[6:7], v[12:13] op_sel:[0,1]
	global_store_short v[58:59], v3, off offset:2048
	global_store_short_d16_hi v[58:59], v3, off offset:2176
	v_pk_fma_f32 v[24:25], v[4:5], v[12:13], v[22:23] neg_lo:[0,0,1] neg_hi:[0,0,1]
	v_pk_fma_f32 v[12:13], v[4:5], v[12:13], v[22:23] op_sel_hi:[1,0,1]
	s_nop 0
	v_mov_b32_e32 v25, v13
	v_pk_add_f32 v[12:13], v[24:25], v[34:35]
	v_cvt_pk_bf16_f32 v3, v12, v13
	v_pk_mul_f32 v[22:23], v[6:7], v[12:13] op_sel:[0,1]
	global_store_short v[58:59], v3, off offset:3328
	global_store_short_d16_hi v[58:59], v3, off offset:3456
	v_pk_fma_f32 v[24:25], v[4:5], v[12:13], v[22:23] neg_lo:[0,0,1] neg_hi:[0,0,1]
	v_pk_fma_f32 v[12:13], v[4:5], v[12:13], v[22:23] op_sel_hi:[1,0,1]
	s_nop 0
	v_mov_b32_e32 v25, v13
	v_pk_add_f32 v[12:13], v[24:25], v[36:37]
	v_cvt_pk_bf16_f32 v3, v12, v13
	v_pk_mul_f32 v[22:23], v[6:7], v[12:13] op_sel:[0,1]
	global_store_short v[60:61], v3, off offset:512
	global_store_short_d16_hi v[60:61], v3, off offset:640
	v_pk_fma_f32 v[24:25], v[4:5], v[12:13], v[22:23] neg_lo:[0,0,1] neg_hi:[0,0,1]
	v_pk_fma_f32 v[12:13], v[4:5], v[12:13], v[22:23] op_sel_hi:[1,0,1]
	s_nop 0
	v_mov_b32_e32 v25, v13
	v_pk_add_f32 v[12:13], v[24:25], v[38:39]
	v_cvt_pk_bf16_f32 v3, v12, v13
	v_pk_mul_f32 v[22:23], v[6:7], v[12:13] op_sel:[0,1]
	global_store_short v[60:61], v3, off offset:1792
	global_store_short_d16_hi v[60:61], v3, off offset:1920
	v_pk_fma_f32 v[24:25], v[4:5], v[12:13], v[22:23] neg_lo:[0,0,1] neg_hi:[0,0,1]
	v_pk_fma_f32 v[12:13], v[4:5], v[12:13], v[22:23] op_sel_hi:[1,0,1]
	s_nop 0
	v_mov_b32_e32 v25, v13
	v_pk_add_f32 v[12:13], v[24:25], v[40:41]
	s_waitcnt vmcnt(16)
	v_lshl_add_u64 v[14:15], s[76:77], 0, v[10:11]
	global_load_dword v26, v[14:15], off offset:-2048
	global_load_dword v27, v[14:15], off offset:-1792
	global_load_dword v28, v[14:15], off offset:-1536
	global_load_dword v29, v[14:15], off offset:-1280
	global_load_dword v30, v[14:15], off offset:-1024
	global_load_dword v31, v[14:15], off offset:-768
	global_load_dword v32, v[14:15], off offset:-512
	global_load_dword v33, v[14:15], off offset:-256
	global_load_dword v34, v[14:15], off
	global_load_dword v35, v[14:15], off offset:256
	global_load_dword v36, v[14:15], off offset:512
	global_load_dword v37, v[14:15], off offset:768
	global_load_dword v38, v[14:15], off offset:1024
	global_load_dword v39, v[14:15], off offset:1280
	global_load_dword v40, v[14:15], off offset:1536
	global_load_dword v41, v[14:15], off offset:1792
	v_lshl_add_u64 v[10:11], v[10:11], 0, s[12:13]
	v_lshl_add_u64 v[16:17], s[76:77], 0, v[8:9]
	v_add_co_u32_e32 v20, vcc, 0xfa00000, v16
	s_mov_b32 s5, 0xfa01000
	s_nop 0
	v_addc_co_u32_e32 v21, vcc, 0, v17, vcc
	v_add_co_u32_e32 v58, vcc, s5, v16
	s_mov_b32 s5, 0xfa02000
	s_nop 0
	v_addc_co_u32_e32 v59, vcc, 0, v17, vcc
	v_add_co_u32_e32 v60, vcc, s5, v16
	s_nop 1
	v_addc_co_u32_e32 v61, vcc, 0, v17, vcc
	v_lshl_add_u64 v[8:9], v[8:9], 0, s[62:63]
	v_cvt_pk_bf16_f32 v3, v12, v13
	v_pk_mul_f32 v[22:23], v[6:7], v[12:13] op_sel:[0,1]
	global_store_short v[20:21], v3, off offset:1024
	global_store_short_d16_hi v[20:21], v3, off offset:1152
	v_pk_fma_f32 v[24:25], v[4:5], v[12:13], v[22:23] neg_lo:[0,0,1] neg_hi:[0,0,1]
	v_pk_fma_f32 v[12:13], v[4:5], v[12:13], v[22:23] op_sel_hi:[1,0,1]
	s_nop 0
	v_mov_b32_e32 v25, v13
	v_pk_add_f32 v[12:13], v[24:25], v[42:43]
	v_cvt_pk_bf16_f32 v3, v12, v13
	v_pk_mul_f32 v[22:23], v[6:7], v[12:13] op_sel:[0,1]
	global_store_short v[20:21], v3, off offset:2304
	global_store_short_d16_hi v[20:21], v3, off offset:2432
	v_pk_fma_f32 v[24:25], v[4:5], v[12:13], v[22:23] neg_lo:[0,0,1] neg_hi:[0,0,1]
	v_pk_fma_f32 v[12:13], v[4:5], v[12:13], v[22:23] op_sel_hi:[1,0,1]
	s_nop 0
	v_mov_b32_e32 v25, v13
	v_pk_add_f32 v[12:13], v[24:25], v[44:45]
	v_cvt_pk_bf16_f32 v3, v12, v13
	v_pk_mul_f32 v[22:23], v[6:7], v[12:13] op_sel:[0,1]
	global_store_short v[20:21], v3, off offset:3584
	global_store_short_d16_hi v[20:21], v3, off offset:3712
	v_pk_fma_f32 v[24:25], v[4:5], v[12:13], v[22:23] neg_lo:[0,0,1] neg_hi:[0,0,1]
	v_pk_fma_f32 v[12:13], v[4:5], v[12:13], v[22:23] op_sel_hi:[1,0,1]
	s_nop 0
	v_mov_b32_e32 v25, v13
	v_pk_add_f32 v[12:13], v[24:25], v[46:47]
	v_cvt_pk_bf16_f32 v3, v12, v13
	v_pk_mul_f32 v[22:23], v[6:7], v[12:13] op_sel:[0,1]
	global_store_short v[58:59], v3, off offset:768
	global_store_short_d16_hi v[58:59], v3, off offset:896
	v_pk_fma_f32 v[24:25], v[4:5], v[12:13], v[22:23] neg_lo:[0,0,1] neg_hi:[0,0,1]
	v_pk_fma_f32 v[12:13], v[4:5], v[12:13], v[22:23] op_sel_hi:[1,0,1]
	s_nop 0
	v_mov_b32_e32 v25, v13
	v_pk_add_f32 v[12:13], v[24:25], v[48:49]
	v_cvt_pk_bf16_f32 v3, v12, v13
	v_pk_mul_f32 v[22:23], v[6:7], v[12:13] op_sel:[0,1]
	global_store_short v[58:59], v3, off offset:2048
	global_store_short_d16_hi v[58:59], v3, off offset:2176
	v_pk_fma_f32 v[24:25], v[4:5], v[12:13], v[22:23] neg_lo:[0,0,1] neg_hi:[0,0,1]
	v_pk_fma_f32 v[12:13], v[4:5], v[12:13], v[22:23] op_sel_hi:[1,0,1]
	s_nop 0
	v_mov_b32_e32 v25, v13
	v_pk_add_f32 v[12:13], v[24:25], v[50:51]
	v_cvt_pk_bf16_f32 v3, v12, v13
	v_pk_mul_f32 v[22:23], v[6:7], v[12:13] op_sel:[0,1]
	global_store_short v[58:59], v3, off offset:3328
	global_store_short_d16_hi v[58:59], v3, off offset:3456
	v_pk_fma_f32 v[24:25], v[4:5], v[12:13], v[22:23] neg_lo:[0,0,1] neg_hi:[0,0,1]
	v_pk_fma_f32 v[12:13], v[4:5], v[12:13], v[22:23] op_sel_hi:[1,0,1]
	s_nop 0
	v_mov_b32_e32 v25, v13
	v_pk_add_f32 v[12:13], v[24:25], v[52:53]
	v_cvt_pk_bf16_f32 v3, v12, v13
	v_pk_mul_f32 v[22:23], v[6:7], v[12:13] op_sel:[0,1]
	global_store_short v[60:61], v3, off offset:512
	global_store_short_d16_hi v[60:61], v3, off offset:640
	v_pk_fma_f32 v[24:25], v[4:5], v[12:13], v[22:23] neg_lo:[0,0,1] neg_hi:[0,0,1]
	v_pk_fma_f32 v[12:13], v[4:5], v[12:13], v[22:23] op_sel_hi:[1,0,1]
	s_nop 0
	v_mov_b32_e32 v25, v13
	v_pk_add_f32 v[12:13], v[24:25], v[54:55]
	v_cvt_pk_bf16_f32 v3, v12, v13
	v_pk_mul_f32 v[22:23], v[6:7], v[12:13] op_sel:[0,1]
	global_store_short v[60:61], v3, off offset:1792
	global_store_short_d16_hi v[60:61], v3, off offset:1920
	v_pk_fma_f32 v[24:25], v[4:5], v[12:13], v[22:23] neg_lo:[0,0,1] neg_hi:[0,0,1]
	v_pk_fma_f32 v[12:13], v[4:5], v[12:13], v[22:23] op_sel_hi:[1,0,1]
	s_nop 0
	v_mov_b32_e32 v25, v13
	v_pk_add_f32 v[12:13], v[24:25], v[56:57]
	s_add_i32 s4, s4, -16
	s_cmp_lg_u32 s4, 0
	s_cbranch_scc1 .Lsc_loop
	s_waitcnt vmcnt(0)
	s_add_i32 s2, s2, 8
	s_mul_i32 s4, s2, s78
	v_readlane_b32 s5, v243, 3
	s_add_i32 s4, s4, s5
	s_add_i32 s3, s3, s28
	s_cmpk_gt_i32 s4, 0xff
	s_cbranch_scc0 .LBB0_190
